# C far path branches directly past the always-false rescale test (trimmed wave-uniform branch test)
# speedup vs baseline: 1.0026x; 1.0026x over previous
; template <int MODE>
; __device__ __forceinline__ void partialSM(f32x16& p0, f32x16& p1, float& m_reg, float& mn, float& alpha, int relh, int relw_min, int relw_max, const float* lut) {
;     ...
;         if (__builtin_expect(__all(tmax - m_reg <= THR2), 1)) { mn = m_reg; alpha = 1.f; }
;         else { mn = fmaxf(m_reg, tmax); alpha = __builtin_amdgcn_exp2f(m_reg - mn); m_reg = mn; }
;         const float off = cfar - mn;
; #pragma unroll
;         for (int r = 0; r < 16; ++r) p0[r] = fmaf(p0[r], C, off);
; #pragma unroll
;         for (int r = 0; r < 16; ++r) p1[r] = fmaf(p1[r], C, off);
; #pragma unroll
;         for (int r = 0; r < 16; ++r) p0[r] = __builtin_amdgcn_exp2f(p0[r]);
.LBB0_136:
	s_or_b64 exec, exec, s[66:67]
	s_and_saveexec_b64 s[66:67], s[64:65]
	s_cbranch_execz .LBB0_138
	v_mov_b32_e32 v66, v229
	v_mov_b32_e32 v228, v219
	v_sub_f32_e32 v66, v66, v228
	v_fmamk_f32 v67, v114, 0x3e38aa3b, v66
	v_mov_b32_e32 v114, v66
	v_mov_b32_e32 v226, 1.0
	v_fmamk_f32 v68, v115, 0x3e38aa3b, v66
	v_fmamk_f32 v69, v116, 0x3e38aa3b, v66
	v_fmamk_f32 v70, v117, 0x3e38aa3b, v66
	v_fmamk_f32 v71, v118, 0x3e38aa3b, v66
	v_fmamk_f32 v72, v119, 0x3e38aa3b, v66
	v_fmamk_f32 v73, v120, 0x3e38aa3b, v66
	v_fmamk_f32 v74, v121, 0x3e38aa3b, v66
	v_fmamk_f32 v75, v122, 0x3e38aa3b, v66
	v_fmamk_f32 v76, v123, 0x3e38aa3b, v66
	v_fmamk_f32 v77, v124, 0x3e38aa3b, v66
	v_fmamk_f32 v78, v125, 0x3e38aa3b, v66
	v_fmamk_f32 v79, v126, 0x3e38aa3b, v66
	v_fmamk_f32 v80, v127, 0x3e38aa3b, v66
	v_fmamk_f32 v81, v128, 0x3e38aa3b, v66
	v_fmac_f32_e32 v114, 0x3e38aa3b, v129
	v_fmamk_f32 v97, v113, 0x3e38aa3b, v66
	v_fmamk_f32 v96, v112, 0x3e38aa3b, v66
	v_fmamk_f32 v95, v111, 0x3e38aa3b, v66
	v_fmamk_f32 v94, v110, 0x3e38aa3b, v66
	v_fmamk_f32 v93, v109, 0x3e38aa3b, v66
	v_fmamk_f32 v92, v108, 0x3e38aa3b, v66
	v_fmamk_f32 v91, v107, 0x3e38aa3b, v66
	v_fmamk_f32 v90, v106, 0x3e38aa3b, v66
	v_fmamk_f32 v89, v105, 0x3e38aa3b, v66
	v_fmamk_f32 v88, v104, 0x3e38aa3b, v66
	v_fmamk_f32 v87, v103, 0x3e38aa3b, v66
	v_fmamk_f32 v86, v102, 0x3e38aa3b, v66
	v_fmamk_f32 v85, v101, 0x3e38aa3b, v66
	v_fmamk_f32 v84, v100, 0x3e38aa3b, v66
	v_fmamk_f32 v83, v99, 0x3e38aa3b, v66
	v_fmamk_f32 v82, v98, 0x3e38aa3b, v66
	v_exp_f32_e32 v66, v67
	v_exp_f32_e32 v67, v68
	v_exp_f32_e32 v68, v69
	v_exp_f32_e32 v69, v70
	v_exp_f32_e32 v70, v71
	v_exp_f32_e32 v71, v72
	v_exp_f32_e32 v72, v73
	v_exp_f32_e32 v73, v74
	v_exp_f32_e32 v74, v75
	v_exp_f32_e32 v75, v76
	v_exp_f32_e32 v76, v77
	v_exp_f32_e32 v77, v78
	v_exp_f32_e32 v78, v79
	v_exp_f32_e32 v79, v80
	v_exp_f32_e32 v80, v81
	v_exp_f32_e32 v81, v114
	s_or_b64 exec, exec, s[66:67]
	s_add_i32 s66, s79, 0
	s_branch .LBB0_142

; template <int MODE>
; __device__ __forceinline__ void partialSM(f32x16& p0, f32x16& p1, float& m_reg, float& mn, float& alpha, int relh, int relw_min, int relw_max, const float* lut) {
;     ...
;         if (__builtin_expect(__all(tmax - m_reg <= THR2), 1)) { mn = m_reg; alpha = 1.f; }
;         else { mn = fmaxf(m_reg, tmax); alpha = __builtin_amdgcn_exp2f(m_reg - mn); m_reg = mn; }
;         const float off = cfar - mn;
; #pragma unroll
;         for (int r = 0; r < 16; ++r) p0[r] = fmaf(p0[r], C, off);
; #pragma unroll
;         for (int r = 0; r < 16; ++r) p1[r] = fmaf(p1[r], C, off);
; #pragma unroll
;         for (int r = 0; r < 16; ++r) p0[r] = __builtin_amdgcn_exp2f(p0[r]);
.LBB0_148:
	s_or_b64 exec, exec, s[68:69]
	s_and_saveexec_b64 s[68:69], s[66:67]
	s_cbranch_execz .LBB0_150
	v_mov_b32_e32 v66, v231
	v_mov_b32_e32 v219, v228
	v_sub_f32_e32 v66, v66, v219
	v_fmamk_f32 v67, v114, 0x3e38aa3b, v66
	v_mov_b32_e32 v114, v66
	v_mov_b32_e32 v225, 1.0
	v_fmamk_f32 v68, v115, 0x3e38aa3b, v66
	v_fmamk_f32 v69, v116, 0x3e38aa3b, v66
	v_fmamk_f32 v70, v117, 0x3e38aa3b, v66
	v_fmamk_f32 v71, v118, 0x3e38aa3b, v66
	v_fmamk_f32 v72, v119, 0x3e38aa3b, v66
	v_fmamk_f32 v73, v120, 0x3e38aa3b, v66
	v_fmamk_f32 v74, v121, 0x3e38aa3b, v66
	v_fmamk_f32 v75, v122, 0x3e38aa3b, v66
	v_fmamk_f32 v76, v123, 0x3e38aa3b, v66
	v_fmamk_f32 v77, v124, 0x3e38aa3b, v66
	v_fmamk_f32 v78, v125, 0x3e38aa3b, v66
	v_fmamk_f32 v79, v126, 0x3e38aa3b, v66
	v_fmamk_f32 v80, v127, 0x3e38aa3b, v66
	v_fmamk_f32 v81, v128, 0x3e38aa3b, v66
	v_fmac_f32_e32 v114, 0x3e38aa3b, v129
	v_fmamk_f32 v97, v113, 0x3e38aa3b, v66
	v_fmamk_f32 v96, v112, 0x3e38aa3b, v66
	v_fmamk_f32 v95, v111, 0x3e38aa3b, v66
	v_fmamk_f32 v94, v110, 0x3e38aa3b, v66
	v_fmamk_f32 v93, v109, 0x3e38aa3b, v66
	v_fmamk_f32 v92, v108, 0x3e38aa3b, v66
	v_fmamk_f32 v91, v107, 0x3e38aa3b, v66
	v_fmamk_f32 v90, v106, 0x3e38aa3b, v66
	v_fmamk_f32 v89, v105, 0x3e38aa3b, v66
	v_fmamk_f32 v88, v104, 0x3e38aa3b, v66
	v_fmamk_f32 v87, v103, 0x3e38aa3b, v66
	v_fmamk_f32 v86, v102, 0x3e38aa3b, v66
	v_fmamk_f32 v85, v101, 0x3e38aa3b, v66
	v_fmamk_f32 v84, v100, 0x3e38aa3b, v66
	v_fmamk_f32 v83, v99, 0x3e38aa3b, v66
	v_fmamk_f32 v82, v98, 0x3e38aa3b, v66
	v_exp_f32_e32 v66, v67
	v_exp_f32_e32 v67, v68
	v_exp_f32_e32 v68, v69
	v_exp_f32_e32 v69, v70
	v_exp_f32_e32 v70, v71
	v_exp_f32_e32 v71, v72
	v_exp_f32_e32 v72, v73
	v_exp_f32_e32 v73, v74
	v_exp_f32_e32 v74, v75
	v_exp_f32_e32 v75, v76
	v_exp_f32_e32 v76, v77
	v_exp_f32_e32 v77, v78
	v_exp_f32_e32 v78, v79
	v_exp_f32_e32 v79, v80
	v_exp_f32_e32 v80, v81
	v_exp_f32_e32 v81, v114
	s_or_b64 exec, exec, s[68:69]
	s_add_i32 s68, s80, 0
	s_branch .LBB0_154

; template <int MODE>
; __device__ __forceinline__ void partialSM(f32x16& p0, f32x16& p1, float& m_reg, float& mn, float& alpha, int relh, int relw_min, int relw_max, const float* lut) {
;     ...
;         if (__builtin_expect(__all(tmax - m_reg <= THR2), 1)) { mn = m_reg; alpha = 1.f; }
;         else { mn = fmaxf(m_reg, tmax); alpha = __builtin_amdgcn_exp2f(m_reg - mn); m_reg = mn; }
;         const float off = cfar - mn;
; #pragma unroll
;         for (int r = 0; r < 16; ++r) p0[r] = fmaf(p0[r], C, off);
; #pragma unroll
;         for (int r = 0; r < 16; ++r) p1[r] = fmaf(p1[r], C, off);
; #pragma unroll
;         for (int r = 0; r < 16; ++r) p0[r] = __builtin_amdgcn_exp2f(p0[r]);
.LBB0_181:
	s_or_b64 exec, exec, s[58:59]
	s_and_saveexec_b64 s[58:59], s[0:1]
	s_cbranch_execz .LBB0_183
	v_mov_b32_e32 v66, v232
	v_mov_b32_e32 v231, v222
	v_sub_f32_e32 v66, v66, v231
	v_fmamk_f32 v67, v114, 0x3e38aa3b, v66
	v_mov_b32_e32 v114, v66
	v_mov_b32_e32 v229, 1.0
	v_fmamk_f32 v68, v115, 0x3e38aa3b, v66
	v_fmamk_f32 v69, v116, 0x3e38aa3b, v66
	v_fmamk_f32 v70, v117, 0x3e38aa3b, v66
	v_fmamk_f32 v71, v118, 0x3e38aa3b, v66
	v_fmamk_f32 v72, v119, 0x3e38aa3b, v66
	v_fmamk_f32 v73, v120, 0x3e38aa3b, v66
	v_fmamk_f32 v74, v121, 0x3e38aa3b, v66
	v_fmamk_f32 v75, v122, 0x3e38aa3b, v66
	v_fmamk_f32 v76, v123, 0x3e38aa3b, v66
	v_fmamk_f32 v77, v124, 0x3e38aa3b, v66
	v_fmamk_f32 v78, v125, 0x3e38aa3b, v66
	v_fmamk_f32 v79, v126, 0x3e38aa3b, v66
	v_fmamk_f32 v80, v127, 0x3e38aa3b, v66
	v_fmamk_f32 v81, v128, 0x3e38aa3b, v66
	v_fmac_f32_e32 v114, 0x3e38aa3b, v129
	v_fmamk_f32 v97, v113, 0x3e38aa3b, v66
	v_fmamk_f32 v96, v112, 0x3e38aa3b, v66
	v_fmamk_f32 v95, v111, 0x3e38aa3b, v66
	v_fmamk_f32 v94, v110, 0x3e38aa3b, v66
	v_fmamk_f32 v93, v109, 0x3e38aa3b, v66
	v_fmamk_f32 v92, v108, 0x3e38aa3b, v66
	v_fmamk_f32 v91, v107, 0x3e38aa3b, v66
	v_fmamk_f32 v90, v106, 0x3e38aa3b, v66
	v_fmamk_f32 v89, v105, 0x3e38aa3b, v66
	v_fmamk_f32 v88, v104, 0x3e38aa3b, v66
	v_fmamk_f32 v87, v103, 0x3e38aa3b, v66
	v_fmamk_f32 v86, v102, 0x3e38aa3b, v66
	v_fmamk_f32 v85, v101, 0x3e38aa3b, v66
	v_fmamk_f32 v84, v100, 0x3e38aa3b, v66
	v_fmamk_f32 v83, v99, 0x3e38aa3b, v66
	v_fmamk_f32 v82, v98, 0x3e38aa3b, v66
	v_exp_f32_e32 v66, v67
	v_exp_f32_e32 v67, v68
	v_exp_f32_e32 v68, v69
	v_exp_f32_e32 v69, v70
	v_exp_f32_e32 v70, v71
	v_exp_f32_e32 v71, v72
	v_exp_f32_e32 v72, v73
	v_exp_f32_e32 v73, v74
	v_exp_f32_e32 v74, v75
	v_exp_f32_e32 v75, v76
	v_exp_f32_e32 v76, v77
	v_exp_f32_e32 v77, v78
	v_exp_f32_e32 v78, v79
	v_exp_f32_e32 v79, v80
	v_exp_f32_e32 v80, v81
	v_exp_f32_e32 v81, v114
	s_or_b64 exec, exec, s[58:59]
	s_add_i32 s58, s2, 0
	s_branch .LBB0_187

; template <int MODE>
; __device__ __forceinline__ void partialSM(f32x16& p0, f32x16& p1, float& m_reg, float& mn, float& alpha, int relh, int relw_min, int relw_max, const float* lut) {
;     ...
;         if (__builtin_expect(__all(tmax - m_reg <= THR2), 1)) { mn = m_reg; alpha = 1.f; }
;         else { mn = fmaxf(m_reg, tmax); alpha = __builtin_amdgcn_exp2f(m_reg - mn); m_reg = mn; }
;         const float off = cfar - mn;
; #pragma unroll
;         for (int r = 0; r < 16; ++r) p0[r] = fmaf(p0[r], C, off);
; #pragma unroll
;         for (int r = 0; r < 16; ++r) p1[r] = fmaf(p1[r], C, off);
; #pragma unroll
;         for (int r = 0; r < 16; ++r) p0[r] = __builtin_amdgcn_exp2f(p0[r]);
.LBB0_193:
	s_or_b64 exec, exec, s[60:61]
	s_and_saveexec_b64 s[60:61], s[58:59]
	s_cbranch_execz .LBB0_195
	v_mov_b32_e32 v66, v234
	v_mov_b32_e32 v222, v231
	v_sub_f32_e32 v66, v66, v222
	v_fmamk_f32 v67, v114, 0x3e38aa3b, v66
	v_mov_b32_e32 v114, v66
	v_mov_b32_e32 v228, 1.0
	v_fmamk_f32 v68, v115, 0x3e38aa3b, v66
	v_fmamk_f32 v69, v116, 0x3e38aa3b, v66
	v_fmamk_f32 v70, v117, 0x3e38aa3b, v66
	v_fmamk_f32 v71, v118, 0x3e38aa3b, v66
	v_fmamk_f32 v72, v119, 0x3e38aa3b, v66
	v_fmamk_f32 v73, v120, 0x3e38aa3b, v66
	v_fmamk_f32 v74, v121, 0x3e38aa3b, v66
	v_fmamk_f32 v75, v122, 0x3e38aa3b, v66
	v_fmamk_f32 v76, v123, 0x3e38aa3b, v66
	v_fmamk_f32 v77, v124, 0x3e38aa3b, v66
	v_fmamk_f32 v78, v125, 0x3e38aa3b, v66
	v_fmamk_f32 v79, v126, 0x3e38aa3b, v66
	v_fmamk_f32 v80, v127, 0x3e38aa3b, v66
	v_fmamk_f32 v81, v128, 0x3e38aa3b, v66
	v_fmac_f32_e32 v114, 0x3e38aa3b, v129
	v_fmamk_f32 v97, v113, 0x3e38aa3b, v66
	v_fmamk_f32 v96, v112, 0x3e38aa3b, v66
	v_fmamk_f32 v95, v111, 0x3e38aa3b, v66
	v_fmamk_f32 v94, v110, 0x3e38aa3b, v66
	v_fmamk_f32 v93, v109, 0x3e38aa3b, v66
	v_fmamk_f32 v92, v108, 0x3e38aa3b, v66
	v_fmamk_f32 v91, v107, 0x3e38aa3b, v66
	v_fmamk_f32 v90, v106, 0x3e38aa3b, v66
	v_fmamk_f32 v89, v105, 0x3e38aa3b, v66
	v_fmamk_f32 v88, v104, 0x3e38aa3b, v66
	v_fmamk_f32 v87, v103, 0x3e38aa3b, v66
	v_fmamk_f32 v86, v102, 0x3e38aa3b, v66
	v_fmamk_f32 v85, v101, 0x3e38aa3b, v66
	v_fmamk_f32 v84, v100, 0x3e38aa3b, v66
	v_fmamk_f32 v83, v99, 0x3e38aa3b, v66
	v_fmamk_f32 v82, v98, 0x3e38aa3b, v66
	v_exp_f32_e32 v66, v67
	v_exp_f32_e32 v67, v68
	v_exp_f32_e32 v68, v69
	v_exp_f32_e32 v69, v70
	v_exp_f32_e32 v70, v71
	v_exp_f32_e32 v71, v72
	v_exp_f32_e32 v72, v73
	v_exp_f32_e32 v73, v74
	v_exp_f32_e32 v74, v75
	v_exp_f32_e32 v75, v76
	v_exp_f32_e32 v76, v77
	v_exp_f32_e32 v77, v78
	v_exp_f32_e32 v78, v79
	v_exp_f32_e32 v79, v80
	v_exp_f32_e32 v80, v81
	v_exp_f32_e32 v81, v114
	s_or_b64 exec, exec, s[60:61]
	s_add_i32 s60, s66, 0
	s_branch .LBB0_199
